# attention item remap: fewest-stage items (s8 6,7) to the late V^T group, most-stage items to the light-ssd group
# speedup vs baseline: 1.0028x; 1.0028x over previous
.LBB0_622:
	v_readlane_b32 s0, v255, 16
	v_readlane_b32 s1, v255, 17
	s_and_b64 vcc, exec, s[0:1]
	s_cbranch_vccnz .LBB0_703
	v_readlane_b32 s0, v255, 18
	v_readlane_b32 s1, v255, 19
	v_readlane_b32 s1, v254, 60
	s_mov_b32 s4, s0
	s_lshl_b32 s34, s0, 6
	v_sub_f32_e64 v1, 1.0, s1
	s_mov_b32 s1, s35
	v_writelane_b32 v255, s4, 18
	v_readlane_b32 s14, v252, 6
	s_lshl_b32 s10, s0, 5
	v_writelane_b32 v255, s5, 19
	s_lshl_b64 s[0:1], s[0:1], 7
	s_lshl_b64 s[24:25], s[34:35], 2
	s_and_b32 s84, s14, 31
	s_lshr_b32 s85, s84, 3
	s_lshl_b32 s85, s85, 2
	s_mov_b32 s86, 0x4260
	s_lshr_b32 s86, s86, s85
	s_and_b32 s86, s86, 15
	s_bfe_u32 s87, s84, 0x10002
	s_add_i32 s86, s86, s87
	s_and_b32 s87, s84, 3
	s_lshl_b32 s87, s87, 3
	s_andn2_b32 s14, s14, 31
	s_or_b32 s14, s14, s86
	s_or_b32 s14, s14, s87
	s_mov_b32 s11, s14
	s_branch .LBB0_626
